# v13: v7 + phase0 GEMV loop double-buffered weight rows (instance 1)
# speedup vs baseline: 1.0048x; 1.0048x over previous
; __device__ __forceinline__ void phase0(int wv, const Params& p, LAS unsigned char* lds, int cb_first, int cb_stride, int cb_lo, int cb_hi, bool do_rope) {
;     ...
;         const int l = cb / 96, nb = cb % 96, nl = tid & 63, ks = tid >> 6;
;         const float* w = p.ada_w + ((size_t)l * 1024 + ks * 128) * 6144 + nb * 64 + nl;
;         float acc[9];
; #pragma unroll
;         for (int i = 0; i < 9; ++i) acc[i] = 0.f;
;         for (int k0 = 0; k0 < 128; k0 += 16) { float wq[16];
; #pragma unroll
;             for (int u = 0; u < 16; ++u) wq[u] = w[(size_t)(k0 + u) * 6144];
; #pragma unroll
;             for (int u = 0; u < 16; ++u)
; #pragma unroll
;                 for (int i = 0; i < 9; ++i) acc[i] += sc[i * 1024 + ks * 128 + k0 + u] * wq[u]; }
.LBB0_18:
	s_or_b64 exec, exec, s[40:41]
	s_mul_hi_i32 s16, s52, 0x2aaaaaab
	s_lshr_b32 s17, s16, 31
	s_ashr_i32 s16, s16, 4
	s_add_i32 s20, s16, s17
	s_mul_i32 s16, s20, 0x60
	s_ashr_i32 s21, s20, 31
	s_sub_i32 s18, s52, s16
	s_lshl_b64 s[16:17], s[20:21], 10
	v_lshl_add_u64 v[0:1], s[16:17], 0, v[120:121]
	v_mov_b64_e32 v[2:3], s[26:27]
	v_mad_u64_u32 v[2:3], s[16:17], v0, s51, v[2:3]
	s_lshl_b32 s40, s18, 6
	v_mad_i32_i24 v3, v1, s51, v3
	s_ashr_i32 s41, s40, 31
	v_lshl_add_u64 v[0:1], s[40:41], 2, v[2:3]
	v_mov_b32_e32 v127, v123
	v_mov_b32_e32 v130, 0
	v_lshl_add_u64 v[128:129], v[0:1], 0, v[126:127]
	s_mov_b32 s21, -16
	v_mov_b32_e32 v122, v119
	v_mov_b32_e32 v131, v130
	v_mov_b32_e32 v132, v130
	v_mov_b32_e32 v133, v130
	v_mov_b32_e32 v134, v130
	v_mov_b32_e32 v135, v130
	v_mov_b32_e32 v136, v130
	v_mov_b32_e32 v137, v130
	v_mov_b32_e32 v127, v130
	s_waitcnt lgkmcnt(0)
	s_barrier
	s_mov_b32 s18, 0x6000
	s_mov_b32 s19, 0
	global_load_dword v0, v[128:129], off
	v_lshl_add_u64 v[128:129], v[128:129], 0, s[18:19]
	global_load_dword v1, v[128:129], off
	v_lshl_add_u64 v[128:129], v[128:129], 0, s[18:19]
	global_load_dword v2, v[128:129], off
	v_lshl_add_u64 v[128:129], v[128:129], 0, s[18:19]
	global_load_dword v3, v[128:129], off
	v_lshl_add_u64 v[128:129], v[128:129], 0, s[18:19]
	global_load_dword v4, v[128:129], off
	v_lshl_add_u64 v[128:129], v[128:129], 0, s[18:19]
	global_load_dword v5, v[128:129], off
	v_lshl_add_u64 v[128:129], v[128:129], 0, s[18:19]
	global_load_dword v6, v[128:129], off
	v_lshl_add_u64 v[128:129], v[128:129], 0, s[18:19]
	global_load_dword v7, v[128:129], off
	v_lshl_add_u64 v[128:129], v[128:129], 0, s[18:19]
	global_load_dword v8, v[128:129], off
	v_lshl_add_u64 v[128:129], v[128:129], 0, s[18:19]
	global_load_dword v9, v[128:129], off
	v_lshl_add_u64 v[128:129], v[128:129], 0, s[18:19]
	global_load_dword v10, v[128:129], off
	v_lshl_add_u64 v[128:129], v[128:129], 0, s[18:19]
	global_load_dword v11, v[128:129], off
	v_lshl_add_u64 v[128:129], v[128:129], 0, s[18:19]
	global_load_dword v12, v[128:129], off
	v_lshl_add_u64 v[128:129], v[128:129], 0, s[18:19]
	global_load_dword v13, v[128:129], off
	v_lshl_add_u64 v[128:129], v[128:129], 0, s[18:19]
	global_load_dword v14, v[128:129], off
	v_lshl_add_u64 v[128:129], v[128:129], 0, s[18:19]
	global_load_dword v15, v[128:129], off
	v_lshl_add_u64 v[128:129], v[128:129], 0, s[18:19]
.LBB0_19:
	global_load_dword v16, v[128:129], off
	v_lshl_add_u64 v[128:129], v[128:129], 0, s[18:19]
	global_load_dword v17, v[128:129], off
	v_lshl_add_u64 v[128:129], v[128:129], 0, s[18:19]
	global_load_dword v18, v[128:129], off
	v_lshl_add_u64 v[128:129], v[128:129], 0, s[18:19]
	global_load_dword v19, v[128:129], off
	v_lshl_add_u64 v[128:129], v[128:129], 0, s[18:19]
	global_load_dword v20, v[128:129], off
	v_lshl_add_u64 v[128:129], v[128:129], 0, s[18:19]
	global_load_dword v21, v[128:129], off
	v_lshl_add_u64 v[128:129], v[128:129], 0, s[18:19]
	global_load_dword v22, v[128:129], off
	v_lshl_add_u64 v[128:129], v[128:129], 0, s[18:19]
	global_load_dword v23, v[128:129], off
	v_lshl_add_u64 v[128:129], v[128:129], 0, s[18:19]
	global_load_dword v24, v[128:129], off
	v_lshl_add_u64 v[128:129], v[128:129], 0, s[18:19]
	global_load_dword v25, v[128:129], off
	v_lshl_add_u64 v[128:129], v[128:129], 0, s[18:19]
	global_load_dword v26, v[128:129], off
	v_lshl_add_u64 v[128:129], v[128:129], 0, s[18:19]
	global_load_dword v27, v[128:129], off
	v_lshl_add_u64 v[128:129], v[128:129], 0, s[18:19]
	global_load_dword v28, v[128:129], off
	v_lshl_add_u64 v[128:129], v[128:129], 0, s[18:19]
	global_load_dword v29, v[128:129], off
	v_lshl_add_u64 v[128:129], v[128:129], 0, s[18:19]
	global_load_dword v30, v[128:129], off
	v_lshl_add_u64 v[128:129], v[128:129], 0, s[18:19]
	global_load_dword v31, v[128:129], off
	v_lshl_add_u64 v[128:129], v[128:129], 0, s[18:19]
	ds_read_b128 v[32:35], v122 offset:0
	ds_read_b128 v[36:39], v122 offset:4096
	ds_read_b128 v[40:43], v122 offset:8192
	ds_read_b128 v[44:47], v122 offset:12288
	ds_read_b128 v[48:51], v122 offset:16384
	ds_read_b128 v[52:55], v122 offset:20480
	ds_read_b128 v[56:59], v122 offset:24576
	ds_read_b128 v[60:63], v122 offset:28672
	ds_read_b128 v[64:67], v122 offset:32768
	s_waitcnt vmcnt(16)
	s_waitcnt lgkmcnt(0)
	ds_read_b128 v[68:71], v122 offset:16
	ds_read_b128 v[72:75], v122 offset:4112
	ds_read_b128 v[76:79], v122 offset:8208
	ds_read_b128 v[80:83], v122 offset:12304
	ds_read_b128 v[84:87], v122 offset:16400
	ds_read_b128 v[88:91], v122 offset:20496
	ds_read_b128 v[92:95], v122 offset:24592
	ds_read_b128 v[96:99], v122 offset:28688
	ds_read_b128 v[100:103], v122 offset:32784
	v_fmac_f32_e32 v130, v0, v32
	v_fmac_f32_e32 v131, v0, v36
	v_fmac_f32_e32 v132, v0, v40
	v_fmac_f32_e32 v133, v0, v44
	v_fmac_f32_e32 v134, v0, v48
	v_fmac_f32_e32 v135, v0, v52
	v_fmac_f32_e32 v136, v0, v56
	v_fmac_f32_e32 v137, v0, v60
	v_fmac_f32_e32 v127, v0, v64
	v_fmac_f32_e32 v130, v1, v33
	v_fmac_f32_e32 v131, v1, v37
	v_fmac_f32_e32 v132, v1, v41
	v_fmac_f32_e32 v133, v1, v45
	v_fmac_f32_e32 v134, v1, v49
	v_fmac_f32_e32 v135, v1, v53
	v_fmac_f32_e32 v136, v1, v57
	v_fmac_f32_e32 v137, v1, v61
	v_fmac_f32_e32 v127, v1, v65
	v_fmac_f32_e32 v130, v2, v34
	v_fmac_f32_e32 v131, v2, v38
	v_fmac_f32_e32 v132, v2, v42
	v_fmac_f32_e32 v133, v2, v46
	v_fmac_f32_e32 v134, v2, v50
	v_fmac_f32_e32 v135, v2, v54
	v_fmac_f32_e32 v136, v2, v58
	v_fmac_f32_e32 v137, v2, v62
	v_fmac_f32_e32 v127, v2, v66
	v_fmac_f32_e32 v130, v3, v35
	v_fmac_f32_e32 v131, v3, v39
	v_fmac_f32_e32 v132, v3, v43
	v_fmac_f32_e32 v133, v3, v47
	v_fmac_f32_e32 v134, v3, v51
	v_fmac_f32_e32 v135, v3, v55
	v_fmac_f32_e32 v136, v3, v59
	v_fmac_f32_e32 v137, v3, v63
	v_fmac_f32_e32 v127, v3, v67
	s_waitcnt lgkmcnt(0)
; __device__ __forceinline__ void phase0(int wv, const Params& p, LAS unsigned char* lds, int cb_first, int cb_stride, int cb_lo, int cb_hi, bool do_rope) {
;     ...
;         for (int k0 = 0; k0 < 128; k0 += 16) { float wq[16];
; #pragma unroll
;             for (int u = 0; u < 16; ++u) wq[u] = w[(size_t)(k0 + u) * 6144];
; #pragma unroll
;             for (int u = 0; u < 16; ++u)
; #pragma unroll
;                 for (int i = 0; i < 9; ++i) acc[i] += sc[i * 1024 + ks * 128 + k0 + u] * wq[u]; }
	ds_read_b128 v[32:35], v122 offset:32
	ds_read_b128 v[36:39], v122 offset:4128
	ds_read_b128 v[40:43], v122 offset:8224
	ds_read_b128 v[44:47], v122 offset:12320
	ds_read_b128 v[48:51], v122 offset:16416
	ds_read_b128 v[52:55], v122 offset:20512
	ds_read_b128 v[56:59], v122 offset:24608
	ds_read_b128 v[60:63], v122 offset:28704
	ds_read_b128 v[64:67], v122 offset:32800
	v_fmac_f32_e32 v130, v4, v68
	v_fmac_f32_e32 v131, v4, v72
	v_fmac_f32_e32 v132, v4, v76
	v_fmac_f32_e32 v133, v4, v80
	v_fmac_f32_e32 v134, v4, v84
	v_fmac_f32_e32 v135, v4, v88
	v_fmac_f32_e32 v136, v4, v92
	v_fmac_f32_e32 v137, v4, v96
	v_mul_f32_e32 v104, v4, v100
	v_add_f32_e32 v127, v127, v104
	v_fmac_f32_e32 v130, v5, v69
	v_fmac_f32_e32 v131, v5, v73
	v_fmac_f32_e32 v132, v5, v77
	v_fmac_f32_e32 v133, v5, v81
	v_fmac_f32_e32 v134, v5, v85
	v_fmac_f32_e32 v135, v5, v89
	v_fmac_f32_e32 v136, v5, v93
	v_fmac_f32_e32 v137, v5, v97
	v_mul_f32_e32 v104, v5, v101
	v_add_f32_e32 v127, v127, v104
	v_fmac_f32_e32 v130, v6, v70
	v_fmac_f32_e32 v131, v6, v74
	v_fmac_f32_e32 v132, v6, v78
	v_fmac_f32_e32 v133, v6, v82
	v_fmac_f32_e32 v134, v6, v86
	v_fmac_f32_e32 v135, v6, v90
	v_fmac_f32_e32 v136, v6, v94
	v_fmac_f32_e32 v137, v6, v98
	v_mul_f32_e32 v104, v6, v102
	v_add_f32_e32 v127, v127, v104
	v_fmac_f32_e32 v130, v7, v71
	v_fmac_f32_e32 v131, v7, v75
	v_fmac_f32_e32 v132, v7, v79
	v_fmac_f32_e32 v133, v7, v83
	v_fmac_f32_e32 v134, v7, v87
	v_fmac_f32_e32 v135, v7, v91
	v_fmac_f32_e32 v136, v7, v95
	v_fmac_f32_e32 v137, v7, v99
	v_mul_f32_e32 v104, v7, v103
	v_add_f32_e32 v127, v127, v104
	s_waitcnt lgkmcnt(0)
	ds_read_b128 v[68:71], v122 offset:48
	ds_read_b128 v[72:75], v122 offset:4144
	ds_read_b128 v[76:79], v122 offset:8240
	ds_read_b128 v[80:83], v122 offset:12336
	ds_read_b128 v[84:87], v122 offset:16432
	ds_read_b128 v[88:91], v122 offset:20528
	ds_read_b128 v[92:95], v122 offset:24624
	ds_read_b128 v[96:99], v122 offset:28720
	ds_read_b128 v[100:103], v122 offset:32816
	v_fmac_f32_e32 v130, v8, v32
	v_fmac_f32_e32 v131, v8, v36
	v_fmac_f32_e32 v132, v8, v40
	v_fmac_f32_e32 v133, v8, v44
	v_fmac_f32_e32 v134, v8, v48
	v_fmac_f32_e32 v135, v8, v52
	v_fmac_f32_e32 v136, v8, v56
	v_fmac_f32_e32 v137, v8, v60
	v_mul_f32_e32 v104, v8, v64
	v_add_f32_e32 v127, v127, v104
	v_fmac_f32_e32 v130, v9, v33
	v_fmac_f32_e32 v131, v9, v37
	v_fmac_f32_e32 v132, v9, v41
	v_fmac_f32_e32 v133, v9, v45
	v_fmac_f32_e32 v134, v9, v49
	v_fmac_f32_e32 v135, v9, v53
	v_fmac_f32_e32 v136, v9, v57
	v_fmac_f32_e32 v137, v9, v61
	v_mul_f32_e32 v104, v9, v65
	v_add_f32_e32 v127, v127, v104
	v_fmac_f32_e32 v130, v10, v34
	v_fmac_f32_e32 v131, v10, v38
	v_fmac_f32_e32 v132, v10, v42
	v_fmac_f32_e32 v133, v10, v46
	v_fmac_f32_e32 v134, v10, v50
	v_fmac_f32_e32 v135, v10, v54
	v_fmac_f32_e32 v136, v10, v58
	v_fmac_f32_e32 v137, v10, v62
	v_mul_f32_e32 v104, v10, v66
	v_add_f32_e32 v127, v127, v104
	v_fmac_f32_e32 v130, v11, v35
	v_fmac_f32_e32 v131, v11, v39
	v_fmac_f32_e32 v132, v11, v43
	v_fmac_f32_e32 v133, v11, v47
	v_fmac_f32_e32 v134, v11, v51
	v_fmac_f32_e32 v135, v11, v55
	v_fmac_f32_e32 v136, v11, v59
	v_fmac_f32_e32 v137, v11, v63
	v_mul_f32_e32 v104, v11, v67
	v_add_f32_e32 v127, v127, v104
	s_waitcnt lgkmcnt(0)
	v_fmac_f32_e32 v130, v12, v68
	v_fmac_f32_e32 v131, v12, v72
	v_fmac_f32_e32 v132, v12, v76
	v_fmac_f32_e32 v133, v12, v80
	v_fmac_f32_e32 v134, v12, v84
	v_fmac_f32_e32 v135, v12, v88
	v_fmac_f32_e32 v136, v12, v92
	v_fmac_f32_e32 v137, v12, v96
	v_mul_f32_e32 v104, v12, v100
	v_add_f32_e32 v127, v127, v104
	v_fmac_f32_e32 v130, v13, v69
	v_fmac_f32_e32 v131, v13, v73
	v_fmac_f32_e32 v132, v13, v77
	v_fmac_f32_e32 v133, v13, v81
	v_fmac_f32_e32 v134, v13, v85
	v_fmac_f32_e32 v135, v13, v89
	v_fmac_f32_e32 v136, v13, v93
	v_fmac_f32_e32 v137, v13, v97
	v_mul_f32_e32 v104, v13, v101
	v_add_f32_e32 v127, v127, v104
	v_fmac_f32_e32 v130, v14, v70
	v_fmac_f32_e32 v131, v14, v74
	v_fmac_f32_e32 v132, v14, v78
	v_fmac_f32_e32 v133, v14, v82
	v_fmac_f32_e32 v134, v14, v86
	v_fmac_f32_e32 v135, v14, v90
	v_fmac_f32_e32 v136, v14, v94
	v_fmac_f32_e32 v137, v14, v98
	v_mul_f32_e32 v104, v14, v102
	v_add_f32_e32 v127, v127, v104
	v_fmac_f32_e32 v130, v15, v71
	v_fmac_f32_e32 v131, v15, v75
	v_fmac_f32_e32 v132, v15, v79
	v_fmac_f32_e32 v133, v15, v83
	v_fmac_f32_e32 v134, v15, v87
	v_fmac_f32_e32 v135, v15, v91
	v_fmac_f32_e32 v136, v15, v95
	v_fmac_f32_e32 v137, v15, v99
	v_mul_f32_e32 v104, v15, v103
	v_add_f32_e32 v127, v127, v104
	v_add_u32_e32 v122, 64, v122
	s_add_i32 s21, s21, 32
	s_cmpk_gt_u32 s21, 0x6f
	s_cbranch_scc1 .Lp0a_last
; __device__ __forceinline__ void phase0(int wv, const Params& p, LAS unsigned char* lds, int cb_first, int cb_stride, int cb_lo, int cb_hi, bool do_rope) {
;     ...
;         for (int k0 = 0; k0 < 128; k0 += 16) { float wq[16];
; #pragma unroll
;             for (int u = 0; u < 16; ++u) wq[u] = w[(size_t)(k0 + u) * 6144];
; #pragma unroll
;             for (int u = 0; u < 16; ++u)
; #pragma unroll
;                 for (int i = 0; i < 9; ++i) acc[i] += sc[i * 1024 + ks * 128 + k0 + u] * wq[u]; }
	global_load_dword v0, v[128:129], off
	v_lshl_add_u64 v[128:129], v[128:129], 0, s[18:19]
	global_load_dword v1, v[128:129], off
	v_lshl_add_u64 v[128:129], v[128:129], 0, s[18:19]
	global_load_dword v2, v[128:129], off
	v_lshl_add_u64 v[128:129], v[128:129], 0, s[18:19]
	global_load_dword v3, v[128:129], off
	v_lshl_add_u64 v[128:129], v[128:129], 0, s[18:19]
	global_load_dword v4, v[128:129], off
	v_lshl_add_u64 v[128:129], v[128:129], 0, s[18:19]
	global_load_dword v5, v[128:129], off
	v_lshl_add_u64 v[128:129], v[128:129], 0, s[18:19]
	global_load_dword v6, v[128:129], off
	v_lshl_add_u64 v[128:129], v[128:129], 0, s[18:19]
	global_load_dword v7, v[128:129], off
	v_lshl_add_u64 v[128:129], v[128:129], 0, s[18:19]
	global_load_dword v8, v[128:129], off
	v_lshl_add_u64 v[128:129], v[128:129], 0, s[18:19]
	global_load_dword v9, v[128:129], off
	v_lshl_add_u64 v[128:129], v[128:129], 0, s[18:19]
	global_load_dword v10, v[128:129], off
	v_lshl_add_u64 v[128:129], v[128:129], 0, s[18:19]
	global_load_dword v11, v[128:129], off
	v_lshl_add_u64 v[128:129], v[128:129], 0, s[18:19]
	global_load_dword v12, v[128:129], off
	v_lshl_add_u64 v[128:129], v[128:129], 0, s[18:19]
	global_load_dword v13, v[128:129], off
	v_lshl_add_u64 v[128:129], v[128:129], 0, s[18:19]
	global_load_dword v14, v[128:129], off
	v_lshl_add_u64 v[128:129], v[128:129], 0, s[18:19]
	global_load_dword v15, v[128:129], off
	v_lshl_add_u64 v[128:129], v[128:129], 0, s[18:19]
	ds_read_b128 v[32:35], v122 offset:0
	ds_read_b128 v[36:39], v122 offset:4096
	ds_read_b128 v[40:43], v122 offset:8192
	ds_read_b128 v[44:47], v122 offset:12288
	ds_read_b128 v[48:51], v122 offset:16384
	ds_read_b128 v[52:55], v122 offset:20480
	ds_read_b128 v[56:59], v122 offset:24576
	ds_read_b128 v[60:63], v122 offset:28672
	ds_read_b128 v[64:67], v122 offset:32768
	s_waitcnt vmcnt(16)
	s_waitcnt lgkmcnt(0)
	ds_read_b128 v[68:71], v122 offset:16
	ds_read_b128 v[72:75], v122 offset:4112
	ds_read_b128 v[76:79], v122 offset:8208
	ds_read_b128 v[80:83], v122 offset:12304
	ds_read_b128 v[84:87], v122 offset:16400
	ds_read_b128 v[88:91], v122 offset:20496
	ds_read_b128 v[92:95], v122 offset:24592
	ds_read_b128 v[96:99], v122 offset:28688
	ds_read_b128 v[100:103], v122 offset:32784
	v_fmac_f32_e32 v130, v16, v32
	v_fmac_f32_e32 v131, v16, v36
	v_fmac_f32_e32 v132, v16, v40
	v_fmac_f32_e32 v133, v16, v44
	v_fmac_f32_e32 v134, v16, v48
	v_fmac_f32_e32 v135, v16, v52
	v_fmac_f32_e32 v136, v16, v56
	v_fmac_f32_e32 v137, v16, v60
	v_fmac_f32_e32 v127, v16, v64
	v_fmac_f32_e32 v130, v17, v33
	v_fmac_f32_e32 v131, v17, v37
	v_fmac_f32_e32 v132, v17, v41
	v_fmac_f32_e32 v133, v17, v45
	v_fmac_f32_e32 v134, v17, v49
	v_fmac_f32_e32 v135, v17, v53
	v_fmac_f32_e32 v136, v17, v57
	v_fmac_f32_e32 v137, v17, v61
	v_fmac_f32_e32 v127, v17, v65
	v_fmac_f32_e32 v130, v18, v34
	v_fmac_f32_e32 v131, v18, v38
	v_fmac_f32_e32 v132, v18, v42
	v_fmac_f32_e32 v133, v18, v46
	v_fmac_f32_e32 v134, v18, v50
	v_fmac_f32_e32 v135, v18, v54
	v_fmac_f32_e32 v136, v18, v58
	v_fmac_f32_e32 v137, v18, v62
	v_fmac_f32_e32 v127, v18, v66
	v_fmac_f32_e32 v130, v19, v35
	v_fmac_f32_e32 v131, v19, v39
	v_fmac_f32_e32 v132, v19, v43
	v_fmac_f32_e32 v133, v19, v47
	v_fmac_f32_e32 v134, v19, v51
	v_fmac_f32_e32 v135, v19, v55
	v_fmac_f32_e32 v136, v19, v59
	v_fmac_f32_e32 v137, v19, v63
	v_fmac_f32_e32 v127, v19, v67
	s_waitcnt lgkmcnt(0)
	ds_read_b128 v[32:35], v122 offset:32
	ds_read_b128 v[36:39], v122 offset:4128
	ds_read_b128 v[40:43], v122 offset:8224
	ds_read_b128 v[44:47], v122 offset:12320
	ds_read_b128 v[48:51], v122 offset:16416
	ds_read_b128 v[52:55], v122 offset:20512
	ds_read_b128 v[56:59], v122 offset:24608
	ds_read_b128 v[60:63], v122 offset:28704
	ds_read_b128 v[64:67], v122 offset:32800
	v_fmac_f32_e32 v130, v20, v68
	v_fmac_f32_e32 v131, v20, v72
	v_fmac_f32_e32 v132, v20, v76
	v_fmac_f32_e32 v133, v20, v80
	v_fmac_f32_e32 v134, v20, v84
	v_fmac_f32_e32 v135, v20, v88
	v_fmac_f32_e32 v136, v20, v92
	v_fmac_f32_e32 v137, v20, v96
	v_mul_f32_e32 v104, v20, v100
	v_add_f32_e32 v127, v127, v104
	v_fmac_f32_e32 v130, v21, v69
	v_fmac_f32_e32 v131, v21, v73
	v_fmac_f32_e32 v132, v21, v77
	v_fmac_f32_e32 v133, v21, v81
	v_fmac_f32_e32 v134, v21, v85
	v_fmac_f32_e32 v135, v21, v89
	v_fmac_f32_e32 v136, v21, v93
	v_fmac_f32_e32 v137, v21, v97
	v_mul_f32_e32 v104, v21, v101
	v_add_f32_e32 v127, v127, v104
	v_fmac_f32_e32 v130, v22, v70
	v_fmac_f32_e32 v131, v22, v74
	v_fmac_f32_e32 v132, v22, v78
	v_fmac_f32_e32 v133, v22, v82
	v_fmac_f32_e32 v134, v22, v86
	v_fmac_f32_e32 v135, v22, v90
	v_fmac_f32_e32 v136, v22, v94
	v_fmac_f32_e32 v137, v22, v98
	v_mul_f32_e32 v104, v22, v102
	v_add_f32_e32 v127, v127, v104
	v_fmac_f32_e32 v130, v23, v71
	v_fmac_f32_e32 v131, v23, v75
	v_fmac_f32_e32 v132, v23, v79
	v_fmac_f32_e32 v133, v23, v83
	v_fmac_f32_e32 v134, v23, v87
	v_fmac_f32_e32 v135, v23, v91
	v_fmac_f32_e32 v136, v23, v95
	v_fmac_f32_e32 v137, v23, v99
	v_mul_f32_e32 v104, v23, v103
	v_add_f32_e32 v127, v127, v104
	s_waitcnt lgkmcnt(0)
; __device__ __forceinline__ void phase0(int wv, const Params& p, LAS unsigned char* lds, int cb_first, int cb_stride, int cb_lo, int cb_hi, bool do_rope) {
;     ...
;         for (int k0 = 0; k0 < 128; k0 += 16) { float wq[16];
; #pragma unroll
;             for (int u = 0; u < 16; ++u) wq[u] = w[(size_t)(k0 + u) * 6144];
; #pragma unroll
;             for (int u = 0; u < 16; ++u)
; #pragma unroll
;                 for (int i = 0; i < 9; ++i) acc[i] += sc[i * 1024 + ks * 128 + k0 + u] * wq[u]; }
	ds_read_b128 v[68:71], v122 offset:48
	ds_read_b128 v[72:75], v122 offset:4144
	ds_read_b128 v[76:79], v122 offset:8240
	ds_read_b128 v[80:83], v122 offset:12336
	ds_read_b128 v[84:87], v122 offset:16432
	ds_read_b128 v[88:91], v122 offset:20528
	ds_read_b128 v[92:95], v122 offset:24624
	ds_read_b128 v[96:99], v122 offset:28720
	ds_read_b128 v[100:103], v122 offset:32816
	v_fmac_f32_e32 v130, v24, v32
	v_fmac_f32_e32 v131, v24, v36
	v_fmac_f32_e32 v132, v24, v40
	v_fmac_f32_e32 v133, v24, v44
	v_fmac_f32_e32 v134, v24, v48
	v_fmac_f32_e32 v135, v24, v52
	v_fmac_f32_e32 v136, v24, v56
	v_fmac_f32_e32 v137, v24, v60
	v_mul_f32_e32 v104, v24, v64
	v_add_f32_e32 v127, v127, v104
	v_fmac_f32_e32 v130, v25, v33
	v_fmac_f32_e32 v131, v25, v37
	v_fmac_f32_e32 v132, v25, v41
	v_fmac_f32_e32 v133, v25, v45
	v_fmac_f32_e32 v134, v25, v49
	v_fmac_f32_e32 v135, v25, v53
	v_fmac_f32_e32 v136, v25, v57
	v_fmac_f32_e32 v137, v25, v61
	v_mul_f32_e32 v104, v25, v65
	v_add_f32_e32 v127, v127, v104
	v_fmac_f32_e32 v130, v26, v34
	v_fmac_f32_e32 v131, v26, v38
	v_fmac_f32_e32 v132, v26, v42
	v_fmac_f32_e32 v133, v26, v46
	v_fmac_f32_e32 v134, v26, v50
	v_fmac_f32_e32 v135, v26, v54
	v_fmac_f32_e32 v136, v26, v58
	v_fmac_f32_e32 v137, v26, v62
	v_mul_f32_e32 v104, v26, v66
	v_add_f32_e32 v127, v127, v104
	v_fmac_f32_e32 v130, v27, v35
	v_fmac_f32_e32 v131, v27, v39
	v_fmac_f32_e32 v132, v27, v43
	v_fmac_f32_e32 v133, v27, v47
	v_fmac_f32_e32 v134, v27, v51
	v_fmac_f32_e32 v135, v27, v55
	v_fmac_f32_e32 v136, v27, v59
	v_fmac_f32_e32 v137, v27, v63
	v_mul_f32_e32 v104, v27, v67
	v_add_f32_e32 v127, v127, v104
	s_waitcnt lgkmcnt(0)
	v_fmac_f32_e32 v130, v28, v68
	v_fmac_f32_e32 v131, v28, v72
	v_fmac_f32_e32 v132, v28, v76
	v_fmac_f32_e32 v133, v28, v80
	v_fmac_f32_e32 v134, v28, v84
	v_fmac_f32_e32 v135, v28, v88
	v_fmac_f32_e32 v136, v28, v92
	v_fmac_f32_e32 v137, v28, v96
	v_mul_f32_e32 v104, v28, v100
	v_add_f32_e32 v127, v127, v104
	v_fmac_f32_e32 v130, v29, v69
	v_fmac_f32_e32 v131, v29, v73
	v_fmac_f32_e32 v132, v29, v77
	v_fmac_f32_e32 v133, v29, v81
	v_fmac_f32_e32 v134, v29, v85
	v_fmac_f32_e32 v135, v29, v89
	v_fmac_f32_e32 v136, v29, v93
	v_fmac_f32_e32 v137, v29, v97
	v_mul_f32_e32 v104, v29, v101
	v_add_f32_e32 v127, v127, v104
	v_fmac_f32_e32 v130, v30, v70
	v_fmac_f32_e32 v131, v30, v74
	v_fmac_f32_e32 v132, v30, v78
	v_fmac_f32_e32 v133, v30, v82
	v_fmac_f32_e32 v134, v30, v86
	v_fmac_f32_e32 v135, v30, v90
	v_fmac_f32_e32 v136, v30, v94
	v_fmac_f32_e32 v137, v30, v98
	v_mul_f32_e32 v104, v30, v102
	v_add_f32_e32 v127, v127, v104
	v_fmac_f32_e32 v130, v31, v71
	v_fmac_f32_e32 v131, v31, v75
	v_fmac_f32_e32 v132, v31, v79
	v_fmac_f32_e32 v133, v31, v83
	v_fmac_f32_e32 v134, v31, v87
	v_fmac_f32_e32 v135, v31, v91
	v_fmac_f32_e32 v136, v31, v95
	v_fmac_f32_e32 v137, v31, v99
	v_mul_f32_e32 v104, v31, v103
	v_add_f32_e32 v127, v127, v104
	v_add_u32_e32 v122, 64, v122
	s_branch .LBB0_19
.Lp0a_last:
	ds_read_b128 v[32:35], v122 offset:0
	ds_read_b128 v[36:39], v122 offset:4096
	ds_read_b128 v[40:43], v122 offset:8192
	ds_read_b128 v[44:47], v122 offset:12288
	ds_read_b128 v[48:51], v122 offset:16384
	ds_read_b128 v[52:55], v122 offset:20480
	ds_read_b128 v[56:59], v122 offset:24576
	ds_read_b128 v[60:63], v122 offset:28672
	ds_read_b128 v[64:67], v122 offset:32768
	s_waitcnt vmcnt(0)
	s_waitcnt lgkmcnt(0)
	ds_read_b128 v[68:71], v122 offset:16
	ds_read_b128 v[72:75], v122 offset:4112
	ds_read_b128 v[76:79], v122 offset:8208
	ds_read_b128 v[80:83], v122 offset:12304
	ds_read_b128 v[84:87], v122 offset:16400
	ds_read_b128 v[88:91], v122 offset:20496
	ds_read_b128 v[92:95], v122 offset:24592
	ds_read_b128 v[96:99], v122 offset:28688
	ds_read_b128 v[100:103], v122 offset:32784
	v_fmac_f32_e32 v130, v16, v32
	v_fmac_f32_e32 v131, v16, v36
	v_fmac_f32_e32 v132, v16, v40
	v_fmac_f32_e32 v133, v16, v44
	v_fmac_f32_e32 v134, v16, v48
	v_fmac_f32_e32 v135, v16, v52
	v_fmac_f32_e32 v136, v16, v56
	v_fmac_f32_e32 v137, v16, v60
	v_fmac_f32_e32 v127, v16, v64
	v_fmac_f32_e32 v130, v17, v33
	v_fmac_f32_e32 v131, v17, v37
	v_fmac_f32_e32 v132, v17, v41
	v_fmac_f32_e32 v133, v17, v45
	v_fmac_f32_e32 v134, v17, v49
	v_fmac_f32_e32 v135, v17, v53
	v_fmac_f32_e32 v136, v17, v57
	v_fmac_f32_e32 v137, v17, v61
	v_fmac_f32_e32 v127, v17, v65
	v_fmac_f32_e32 v130, v18, v34
	v_fmac_f32_e32 v131, v18, v38
	v_fmac_f32_e32 v132, v18, v42
	v_fmac_f32_e32 v133, v18, v46
	v_fmac_f32_e32 v134, v18, v50
	v_fmac_f32_e32 v135, v18, v54
	v_fmac_f32_e32 v136, v18, v58
	v_fmac_f32_e32 v137, v18, v62
	v_fmac_f32_e32 v127, v18, v66
	v_fmac_f32_e32 v130, v19, v35
	v_fmac_f32_e32 v131, v19, v39
	v_fmac_f32_e32 v132, v19, v43
	v_fmac_f32_e32 v133, v19, v47
	v_fmac_f32_e32 v134, v19, v51
	v_fmac_f32_e32 v135, v19, v55
	v_fmac_f32_e32 v136, v19, v59
	v_fmac_f32_e32 v137, v19, v63
	v_fmac_f32_e32 v127, v19, v67
	s_waitcnt lgkmcnt(0)
; __device__ __forceinline__ void phase0(int wv, const Params& p, LAS unsigned char* lds, int cb_first, int cb_stride, int cb_lo, int cb_hi, bool do_rope) {
;     ...
;         for (int k0 = 0; k0 < 128; k0 += 16) { float wq[16];
; #pragma unroll
;             for (int u = 0; u < 16; ++u) wq[u] = w[(size_t)(k0 + u) * 6144];
; #pragma unroll
;             for (int u = 0; u < 16; ++u)
; #pragma unroll
;                 for (int i = 0; i < 9; ++i) acc[i] += sc[i * 1024 + ks * 128 + k0 + u] * wq[u]; }
; #pragma unroll
;         for (int i = 0; i < 9; ++i) part[(ks * 9 + i) * 64 + nl] = acc[i];
;         __syncthreads();
;         for (int e = tid; e < 576; e += 512) { const int i = e >> 6, nn = e & 63; float s = 0.f;
; #pragma unroll
;             for (int k2 = 0; k2 < 8; ++k2) s += part[(k2 * 9 + i) * 64 + nn];
;             mod[((size_t)l * 9 + i) * 6144 + nb * 64 + nn] = s + p.ada_b[l * 6144 + nb * 64 + nn]; }
	ds_read_b128 v[32:35], v122 offset:32
	ds_read_b128 v[36:39], v122 offset:4128
	ds_read_b128 v[40:43], v122 offset:8224
	ds_read_b128 v[44:47], v122 offset:12320
	ds_read_b128 v[48:51], v122 offset:16416
	ds_read_b128 v[52:55], v122 offset:20512
	ds_read_b128 v[56:59], v122 offset:24608
	ds_read_b128 v[60:63], v122 offset:28704
	ds_read_b128 v[64:67], v122 offset:32800
	v_fmac_f32_e32 v130, v20, v68
	v_fmac_f32_e32 v131, v20, v72
	v_fmac_f32_e32 v132, v20, v76
	v_fmac_f32_e32 v133, v20, v80
	v_fmac_f32_e32 v134, v20, v84
	v_fmac_f32_e32 v135, v20, v88
	v_fmac_f32_e32 v136, v20, v92
	v_fmac_f32_e32 v137, v20, v96
	v_mul_f32_e32 v104, v20, v100
	v_add_f32_e32 v127, v127, v104
	v_fmac_f32_e32 v130, v21, v69
	v_fmac_f32_e32 v131, v21, v73
	v_fmac_f32_e32 v132, v21, v77
	v_fmac_f32_e32 v133, v21, v81
	v_fmac_f32_e32 v134, v21, v85
	v_fmac_f32_e32 v135, v21, v89
	v_fmac_f32_e32 v136, v21, v93
	v_fmac_f32_e32 v137, v21, v97
	v_mul_f32_e32 v104, v21, v101
	v_add_f32_e32 v127, v127, v104
	v_fmac_f32_e32 v130, v22, v70
	v_fmac_f32_e32 v131, v22, v74
	v_fmac_f32_e32 v132, v22, v78
	v_fmac_f32_e32 v133, v22, v82
	v_fmac_f32_e32 v134, v22, v86
	v_fmac_f32_e32 v135, v22, v90
	v_fmac_f32_e32 v136, v22, v94
	v_fmac_f32_e32 v137, v22, v98
	v_mul_f32_e32 v104, v22, v102
	v_add_f32_e32 v127, v127, v104
	v_fmac_f32_e32 v130, v23, v71
	v_fmac_f32_e32 v131, v23, v75
	v_fmac_f32_e32 v132, v23, v79
	v_fmac_f32_e32 v133, v23, v83
	v_fmac_f32_e32 v134, v23, v87
	v_fmac_f32_e32 v135, v23, v91
	v_fmac_f32_e32 v136, v23, v95
	v_fmac_f32_e32 v137, v23, v99
	v_mul_f32_e32 v104, v23, v103
	v_add_f32_e32 v127, v127, v104
	s_waitcnt lgkmcnt(0)
	ds_read_b128 v[68:71], v122 offset:48
	ds_read_b128 v[72:75], v122 offset:4144
	ds_read_b128 v[76:79], v122 offset:8240
	ds_read_b128 v[80:83], v122 offset:12336
	ds_read_b128 v[84:87], v122 offset:16432
	ds_read_b128 v[88:91], v122 offset:20528
	ds_read_b128 v[92:95], v122 offset:24624
	ds_read_b128 v[96:99], v122 offset:28720
	ds_read_b128 v[100:103], v122 offset:32816
	v_fmac_f32_e32 v130, v24, v32
	v_fmac_f32_e32 v131, v24, v36
	v_fmac_f32_e32 v132, v24, v40
	v_fmac_f32_e32 v133, v24, v44
	v_fmac_f32_e32 v134, v24, v48
	v_fmac_f32_e32 v135, v24, v52
	v_fmac_f32_e32 v136, v24, v56
	v_fmac_f32_e32 v137, v24, v60
	v_mul_f32_e32 v104, v24, v64
	v_add_f32_e32 v127, v127, v104
	v_fmac_f32_e32 v130, v25, v33
	v_fmac_f32_e32 v131, v25, v37
	v_fmac_f32_e32 v132, v25, v41
	v_fmac_f32_e32 v133, v25, v45
	v_fmac_f32_e32 v134, v25, v49
	v_fmac_f32_e32 v135, v25, v53
	v_fmac_f32_e32 v136, v25, v57
	v_fmac_f32_e32 v137, v25, v61
	v_mul_f32_e32 v104, v25, v65
	v_add_f32_e32 v127, v127, v104
	v_fmac_f32_e32 v130, v26, v34
	v_fmac_f32_e32 v131, v26, v38
	v_fmac_f32_e32 v132, v26, v42
	v_fmac_f32_e32 v133, v26, v46
	v_fmac_f32_e32 v134, v26, v50
	v_fmac_f32_e32 v135, v26, v54
	v_fmac_f32_e32 v136, v26, v58
	v_fmac_f32_e32 v137, v26, v62
	v_mul_f32_e32 v104, v26, v66
	v_add_f32_e32 v127, v127, v104
	v_fmac_f32_e32 v130, v27, v35
	v_fmac_f32_e32 v131, v27, v39
	v_fmac_f32_e32 v132, v27, v43
	v_fmac_f32_e32 v133, v27, v47
	v_fmac_f32_e32 v134, v27, v51
	v_fmac_f32_e32 v135, v27, v55
	v_fmac_f32_e32 v136, v27, v59
	v_fmac_f32_e32 v137, v27, v63
	v_mul_f32_e32 v104, v27, v67
	v_add_f32_e32 v127, v127, v104
	s_waitcnt lgkmcnt(0)
	v_fmac_f32_e32 v130, v28, v68
	v_fmac_f32_e32 v131, v28, v72
	v_fmac_f32_e32 v132, v28, v76
	v_fmac_f32_e32 v133, v28, v80
	v_fmac_f32_e32 v134, v28, v84
	v_fmac_f32_e32 v135, v28, v88
	v_fmac_f32_e32 v136, v28, v92
	v_fmac_f32_e32 v137, v28, v96
	v_mul_f32_e32 v104, v28, v100
	v_add_f32_e32 v127, v127, v104
	v_fmac_f32_e32 v130, v29, v69
	v_fmac_f32_e32 v131, v29, v73
	v_fmac_f32_e32 v132, v29, v77
	v_fmac_f32_e32 v133, v29, v81
	v_fmac_f32_e32 v134, v29, v85
	v_fmac_f32_e32 v135, v29, v89
	v_fmac_f32_e32 v136, v29, v93
	v_fmac_f32_e32 v137, v29, v97
	v_mul_f32_e32 v104, v29, v101
	v_add_f32_e32 v127, v127, v104
	v_fmac_f32_e32 v130, v30, v70
	v_fmac_f32_e32 v131, v30, v74
	v_fmac_f32_e32 v132, v30, v78
	v_fmac_f32_e32 v133, v30, v82
	v_fmac_f32_e32 v134, v30, v86
	v_fmac_f32_e32 v135, v30, v90
	v_fmac_f32_e32 v136, v30, v94
	v_fmac_f32_e32 v137, v30, v98
	v_mul_f32_e32 v104, v30, v102
	v_add_f32_e32 v127, v127, v104
	v_fmac_f32_e32 v130, v31, v71
	v_fmac_f32_e32 v131, v31, v75
	v_fmac_f32_e32 v132, v31, v79
	v_fmac_f32_e32 v133, v31, v83
	v_fmac_f32_e32 v134, v31, v87
	v_fmac_f32_e32 v135, v31, v91
	v_fmac_f32_e32 v136, v31, v95
	v_fmac_f32_e32 v137, v31, v99
	v_mul_f32_e32 v104, v31, v103
	v_add_f32_e32 v127, v127, v104
	v_add_u32_e32 v122, 64, v122
	ds_write2st64_b32 v144, v130, v131 offset0:144 offset1:145
	ds_write2st64_b32 v144, v132, v133 offset0:146 offset1:147
	ds_write2st64_b32 v144, v134, v135 offset0:148 offset1:149
	ds_write2st64_b32 v144, v136, v137 offset0:150 offset1:151
	ds_write_b32 v144, v127 offset:38912
	s_waitcnt lgkmcnt(0)
	s_barrier
	s_and_saveexec_b64 s[16:17], s[6:7]
	s_cbranch_execz .LBB0_5
	s_mul_i32 s18, s20, 0x1800
	s_add_i32 s21, s18, s40
	v_or_b32_e32 v0, s21, v118
	v_ashrrev_i32_e32 v1, 31, v0
	s_mul_hi_i32 s19, s20, 9
	s_mul_i32 s18, s20, 9
	v_lshl_add_u64 v[0:1], v[0:1], 2, s[34:35]
	v_lshl_add_u64 v[2:3], s[40:41], 2, v[124:125]
	s_mov_b64 s[20:21], 0
	v_mov_b32_e32 v4, v116
